# v75 = v72 + select scoring: km row streamed through SGPRs (s_load_dwordx8, 3 rotating buffers) as scalar FMA operands instead of 16 broadcast ds_read_b128 per block; same FMA order
# speedup vs baseline: 1.0056x; 1.0056x over previous
.LBB0_164:
	s_ashr_i32 s0, s33, 1
	s_ashr_i32 s1, s0, 31
	s_lshl_b64 s[10:11], s[0:1], 12
	v_readlane_b32 s28, v254, 61
	v_readlane_b32 s29, v254, 62
	s_nop 0
	s_add_u32 s28, s28, s10
	s_addc_u32 s29, s29, s11
	v_lshl_add_u64 v[0:1], v[66:67], 0, s[10:11]
	s_mov_b64 s[6:7], 0
	v_mov_b32_e32 v2, v71
	v_mov_b32_e32 v3, v70
	s_barrier

.LBB0_173:
	s_add_u32 s30, s28, s22
	s_addc_u32 s31, s29, 0
	s_load_dwordx8 s[44:51], s[30:31], 0x0
	s_load_dwordx8 s[76:83], s[30:31], 0x20
	s_load_dwordx8 s[92:99], s[30:31], 0x40
	s_waitcnt lgkmcnt(0)
	v_fma_f32 v127, s44, v76, 0
	v_fmac_f32_e32 v127, s45, v60
	v_fmac_f32_e32 v127, s46, v77
	v_fmac_f32_e32 v127, s47, v61
	v_fmac_f32_e32 v127, s48, v78
	v_fmac_f32_e32 v127, s49, v62
	v_fmac_f32_e32 v127, s50, v79
	v_fmac_f32_e32 v127, s51, v63
	s_load_dwordx8 s[44:51], s[30:31], 0x60
	v_fmac_f32_e32 v127, s76, v80
	v_fmac_f32_e32 v127, s77, v56
	v_fmac_f32_e32 v127, s78, v81
	v_fmac_f32_e32 v127, s79, v57
	v_fmac_f32_e32 v127, s80, v82
	v_fmac_f32_e32 v127, s81, v58
	v_fmac_f32_e32 v127, s82, v83
	v_fmac_f32_e32 v127, s83, v59
	s_load_dwordx8 s[76:83], s[30:31], 0x80
	v_fmac_f32_e32 v127, s92, v84
	v_fmac_f32_e32 v127, s93, v52
	v_fmac_f32_e32 v127, s94, v85
	v_fmac_f32_e32 v127, s95, v53
	v_fmac_f32_e32 v127, s96, v86
	v_fmac_f32_e32 v127, s97, v54
	v_fmac_f32_e32 v127, s98, v87
	v_fmac_f32_e32 v127, s99, v55
	s_load_dwordx8 s[92:99], s[30:31], 0xa0
	s_waitcnt lgkmcnt(0)
	v_fmac_f32_e32 v127, s44, v88
	v_fmac_f32_e32 v127, s45, v48
	v_fmac_f32_e32 v127, s46, v89
	v_fmac_f32_e32 v127, s47, v49
	v_fmac_f32_e32 v127, s48, v90
	v_fmac_f32_e32 v127, s49, v50
	v_fmac_f32_e32 v127, s50, v91
	v_fmac_f32_e32 v127, s51, v51
	s_load_dwordx8 s[44:51], s[30:31], 0xc0
	v_fmac_f32_e32 v127, s76, v92
	v_fmac_f32_e32 v127, s77, v93
	v_fmac_f32_e32 v127, s78, v94
	v_fmac_f32_e32 v127, s79, v95
	v_fmac_f32_e32 v127, s80, v96
	v_fmac_f32_e32 v127, s81, v46
	v_fmac_f32_e32 v127, s82, v97
	v_fmac_f32_e32 v127, s83, v47
	s_load_dwordx8 s[76:83], s[30:31], 0xe0
	v_fmac_f32_e32 v127, s92, v98
	v_fmac_f32_e32 v127, s93, v99
	v_fmac_f32_e32 v127, s94, v100
	v_fmac_f32_e32 v127, s95, v101
	v_fmac_f32_e32 v127, s96, v102
	v_fmac_f32_e32 v127, s97, v103
	v_fmac_f32_e32 v127, s98, v104
	v_fmac_f32_e32 v127, s99, v105
	s_waitcnt lgkmcnt(0)
	v_fmac_f32_e32 v127, s44, v106
	v_fmac_f32_e32 v127, s45, v107
	v_fmac_f32_e32 v127, s46, v108
	v_fmac_f32_e32 v127, s47, v109
	v_mul_f32_e32 v114, s48, v36
	v_mul_f32_e32 v115, s49, v37
	v_add_f32_e32 v114, v114, v127
	v_add_f32_e32 v122, v115, v114
	v_mul_f32_e32 v114, s50, v40
	v_mul_f32_e32 v115, s51, v41
	v_add_f32_e32 v114, v114, v122
	v_add_f32_e32 v122, v115, v114
	v_mul_f32_e32 v118, s76, v38
	v_mul_f32_e32 v119, s77, v39
	v_add_f32_e32 v118, v118, v122
	v_add_f32_e32 v122, v119, v118
	v_mul_f32_e32 v118, s78, v42
	v_mul_f32_e32 v119, s79, v43
	v_add_f32_e32 v118, v118, v122
	v_add_f32_e32 v118, v119, v118
	v_mul_f32_e32 v114, s80, v32
	v_mul_f32_e32 v115, s81, v33
	v_add_f32_e32 v114, v114, v118
	v_add_f32_e32 v118, v115, v114
	v_mul_f32_e32 v114, s82, v44
	v_mul_f32_e32 v115, s83, v45
	v_mov_b32_e32 v116, v110
	v_add_f32_e32 v114, v114, v118
	v_add_f32_e32 v115, v115, v114
	v_cmp_ngt_f32_e32 vcc, v115, v110
	v_mov_b32_e32 v114, s21
	s_and_saveexec_b64 s[6:7], vcc
	s_cbranch_execz .LBB0_172
	v_cmp_ngt_f32_e32 vcc, v115, v111
	v_mov_b32_e32 v116, s21
	s_and_saveexec_b64 s[8:9], vcc
	s_cbranch_execz .LBB0_171
	v_cmp_gt_f32_e32 vcc, v115, v113
	s_and_saveexec_b64 s[18:19], vcc
	s_cbranch_execz .LBB0_170
	v_mov_b32_e32 v35, s21
	v_mov_b32_e32 v113, v115
	s_branch .LBB0_170
